# attention phase: static s_setprio 1 for waves 4-7 (reset to 0 at phase end)
# speedup vs baseline: 1.0102x; 1.0053x over previous
.LBB0_892:
	v_readlane_b32 s32, v252, 5
	s_nop 0
	s_cmp_ge_u32 s32, 0x100
	s_cbranch_scc0 .Lprio_att
	s_setprio 1

.LBB0_1089:
	s_setprio 0
	v_readlane_b32 s0, v255, 8
	s_add_i32 s26, s0, 5
	s_cmp_ge_i32 s26, s93
	s_cbranch_scc1 .LBB0_1145
	s_waitcnt vmcnt(0)
	v_readlane_b32 s0, v252, 3
	v_readlane_b32 s1, v252, 4
	s_and_b64 vcc, exec, s[0:1]
	s_waitcnt lgkmcnt(0)
	s_barrier
	s_cbranch_vccnz .LBB0_1144
	s_mov_b32 s0, -1
	s_nop 0
	v_mbcnt_lo_u32_b32 v0, s0, 0
	v_mbcnt_hi_u32_b32 v0, s0, v0
	v_cmp_eq_u32_e32 vcc, 0, v0
	s_and_saveexec_b64 s[0:1], vcc
	s_cbranch_execz .LBB0_1143
	v_readlane_b32 s4, v254, 31
	s_waitcnt vmcnt(0) expcnt(0) lgkmcnt(0)
	s_nop 0
	v_mov_b32_e32 v0, s4
	ds_read_b32 v2, v0
	v_readlane_b32 s4, v254, 32
	s_waitcnt lgkmcnt(0)
	v_cmp_ne_u32_e32 vcc, 0, v2
	v_mov_b32_e32 v0, s4
	ds_read_b32 v0, v0
	s_cbranch_vccnz .LBB0_1107
	s_mov_b32 s27, 1
	s_branch .LBB0_1095
